# combo15 + fp8 down-projection epilogue: later chunks of each per-column vector requested together with its first chunk (3 instead of 12 drained L2 round trips per unit)
# baseline (speedup 1.0000x reference)
.LBB0_921:
	s_lshr_b32 s10, s87, 4
	s_mulk_i32 s10, 0x4800
	s_add_u32 s8, s8, s10
	s_addc_u32 s9, s9, 0
	s_lshl_b64 s[8:9], s[8:9], 2
	v_readlane_b32 s10, v255, 14
	v_lshlrev_b32_e32 v130, 5, v194
	s_add_u32 s10, s10, s8
	v_readlane_b32 s11, v255, 15
	s_addc_u32 s11, s11, s9
	v_ashrrev_i32_e32 v131, 31, v130
	v_mov_b32_e32 v164, v198
	v_lshl_add_u64 v[166:167], s[10:11], 0, v[130:131]
	global_load_dwordx4 v[132:135], v[166:167], off
	global_load_dwordx4 v[212:215], v[166:167], off offset:16
	global_load_dwordx4 v[216:219], v[166:167], off offset:512
	global_load_dwordx4 v[220:223], v[166:167], off offset:528
	s_add_u32 s50, s16, s4
	v_cndmask_b32_e64 v136, 0, 1, s[66:67]
	s_addc_u32 s51, s17, s5
	v_cmp_ne_u32_e64 s[10:11], 1, v136
	s_andn2_b64 vcc, exec, s[66:67]
	v_lshl_add_u64 v[168:169], s[50:51], 0, v[130:131]
	s_waitcnt vmcnt(0)
	v_pk_mul_f32 v[180:181], v[134:135], v[164:165] op_sel_hi:[1,0]
	v_pk_mul_f32 v[178:179], v[132:133], v[164:165] op_sel_hi:[1,0]
	s_cbranch_vccnz .LBB0_923
	global_load_dwordx4 v[132:135], v[168:169], off
	global_load_dwordx4 v[224:227], v[168:169], off offset:16
	global_load_dwordx4 v[228:231], v[168:169], off offset:512
	global_load_dwordx4 v[232:235], v[168:169], off offset:528
	s_waitcnt vmcnt(0)
	v_pk_mul_f32 v[180:181], v[180:181], v[134:135]
	v_pk_mul_f32 v[178:179], v[178:179], v[132:133]
.LBB0_923:
	v_readlane_b32 s46, v255, 24
	s_add_u32 s8, s46, s8
	v_readlane_b32 s46, v255, 21
	s_addc_u32 s9, s46, s9
	v_readlane_b32 s46, v254, 62
	s_add_u32 s4, s46, s4
	v_readlane_b32 s46, v255, 9
	s_addc_u32 s5, s46, s5
	v_lshl_add_u64 v[170:171], s[8:9], 0, v[130:131]
	v_lshl_add_u64 v[172:173], s[4:5], 0, v[130:131]
	v_mov_b32_e32 v174, 0
	v_cndmask_b32_e64 v131, 0, 1, s[22:23]
	v_cmp_ne_u32_e64 s[4:5], 1, v131
	s_andn2_b64 vcc, exec, s[22:23]
	v_mov_b32_e32 v175, v174
	v_mov_b32_e32 v176, v174
	v_mov_b32_e32 v177, v174
	s_cbranch_vccnz .LBB0_925
	global_load_dwordx4 v[132:135], v[170:171], off
	global_load_dwordx4 v[136:139], v[172:173], off
	global_load_dwordx4 v[236:239], v[170:171], off offset:16
	global_load_dwordx4 v[240:243], v[172:173], off offset:16
	global_load_dwordx4 v[244:247], v[170:171], off offset:512
	global_load_dwordx4 v[248:251], v[172:173], off offset:512
	s_waitcnt vmcnt(0)
	v_pk_add_f32 v[134:135], v[134:135], 1.0 op_sel_hi:[1,0]
	v_pk_add_f32 v[132:133], v[132:133], 1.0 op_sel_hi:[1,0]
	s_waitcnt vmcnt(0)
	v_pk_mul_f32 v[176:177], v[138:139], v[134:135]
	v_pk_mul_f32 v[174:175], v[136:137], v[132:133]
.LBB0_925:
	s_nop 1
	v_mov_b32_e32 v132, v212
	v_mov_b32_e32 v133, v213
	v_mov_b32_e32 v134, v214
	v_mov_b32_e32 v135, v215
	v_mov_b32_e32 v165, v164
	v_mov_b32_e32 v136, v164
	v_mov_b32_e32 v137, v164
	s_and_b64 vcc, exec, s[10:11]
	s_waitcnt vmcnt(0)
	v_pk_mul_f32 v[188:189], v[136:137], v[134:135]
	v_pk_mul_f32 v[186:187], v[164:165], v[132:133]
	s_cbranch_vccnz .LBB0_927
	s_nop 1
	v_mov_b32_e32 v132, v224
	v_mov_b32_e32 v133, v225
	v_mov_b32_e32 v134, v226
	v_mov_b32_e32 v135, v227
	s_waitcnt vmcnt(0)
	v_pk_mul_f32 v[188:189], v[188:189], v[134:135]
	v_pk_mul_f32 v[186:187], v[186:187], v[132:133]
.LBB0_927:
	v_mov_b32_e32 v182, 0
	s_and_b64 vcc, exec, s[4:5]
	v_mov_b32_e32 v183, v182
	v_mov_b32_e32 v184, v182
	v_mov_b32_e32 v185, v182
	s_cbranch_vccnz .LBB0_929
	s_nop 1
	v_mov_b32_e32 v132, v236
	v_mov_b32_e32 v133, v237
	v_mov_b32_e32 v134, v238
	v_mov_b32_e32 v135, v239
	s_nop 1
	v_mov_b32_e32 v136, v240
	v_mov_b32_e32 v137, v241
	v_mov_b32_e32 v138, v242
	v_mov_b32_e32 v139, v243
	s_waitcnt vmcnt(1)
	v_pk_add_f32 v[134:135], v[134:135], 1.0 op_sel_hi:[1,0]
	v_pk_add_f32 v[132:133], v[132:133], 1.0 op_sel_hi:[1,0]
	s_waitcnt vmcnt(0)
	v_pk_mul_f32 v[184:185], v[138:139], v[134:135]
	v_pk_mul_f32 v[182:183], v[136:137], v[132:133]

.LBB0_1029:
	s_nop 1
	v_mov_b32_e32 v74, v216
	v_mov_b32_e32 v75, v217
	v_mov_b32_e32 v76, v218
	v_mov_b32_e32 v77, v219
	v_mov_b32_e32 v78, v164
	v_mov_b32_e32 v79, v164
	s_and_b64 vcc, exec, s[10:11]
	s_waitcnt vmcnt(0)
	v_pk_mul_f32 v[92:93], v[78:79], v[76:77]
	v_pk_mul_f32 v[90:91], v[164:165], v[74:75]
	s_cbranch_vccnz .LBB0_1031
	s_nop 1
	v_mov_b32_e32 v74, v228
	v_mov_b32_e32 v75, v229
	v_mov_b32_e32 v76, v230
	v_mov_b32_e32 v77, v231
	s_waitcnt vmcnt(0)
	v_pk_mul_f32 v[92:93], v[92:93], v[76:77]
	v_pk_mul_f32 v[90:91], v[90:91], v[74:75]
.LBB0_1031:
	v_mov_b32_e32 v74, 0
	s_and_b64 vcc, exec, s[4:5]
	v_mov_b32_e32 v75, v74
	v_mov_b32_e32 v76, v74
	v_mov_b32_e32 v77, v74
	s_cbranch_vccnz .LBB0_1033
	s_nop 1
	v_mov_b32_e32 v74, v244
	v_mov_b32_e32 v75, v245
	v_mov_b32_e32 v76, v246
	v_mov_b32_e32 v77, v247
	s_nop 1
	v_mov_b32_e32 v78, v248
	v_mov_b32_e32 v79, v249
	v_mov_b32_e32 v80, v250
	v_mov_b32_e32 v81, v251
	s_waitcnt vmcnt(1)
	v_pk_add_f32 v[76:77], v[76:77], 1.0 op_sel_hi:[1,0]
	v_pk_add_f32 v[74:75], v[74:75], 1.0 op_sel_hi:[1,0]
	s_waitcnt vmcnt(0)
	v_pk_mul_f32 v[76:77], v[80:81], v[76:77]
	v_pk_mul_f32 v[74:75], v[78:79], v[74:75]
.LBB0_1033:
	s_nop 1
	v_mov_b32_e32 v78, v220
	v_mov_b32_e32 v79, v221
	v_mov_b32_e32 v80, v222
	v_mov_b32_e32 v81, v223
	v_mov_b32_e32 v94, v164
	v_mov_b32_e32 v95, v164
	s_and_b64 vcc, exec, s[10:11]
	s_waitcnt vmcnt(0)
	v_pk_mul_f32 v[96:97], v[94:95], v[80:81]
	v_pk_mul_f32 v[94:95], v[164:165], v[78:79]
	s_cbranch_vccnz .LBB0_1035
	s_nop 1
	v_mov_b32_e32 v78, v232
	v_mov_b32_e32 v79, v233
	v_mov_b32_e32 v80, v234
	v_mov_b32_e32 v81, v235
	s_waitcnt vmcnt(0)
	v_pk_mul_f32 v[96:97], v[96:97], v[80:81]
	v_pk_mul_f32 v[94:95], v[94:95], v[78:79]
